# grid-barrier / last-arriver poll loops: longer back-off between polls (s_sleep 6 instead of 1)
# speedup vs baseline: 1.0065x; 1.0065x over previous
.LBB0_12:
	s_sleep 6
	global_load_dword v2, v0, s[6:7] offset:32 sc1
	s_waitcnt vmcnt(0)
	v_and_b32_e32 v2, 0xffff0000, v2
	v_cmp_ne_u32_e32 vcc, v2, v1
	s_or_b64 s[8:9], vcc, s[8:9]
	s_andn2_b64 exec, exec, s[8:9]
	s_cbranch_execnz .LBB0_12

.LBB0_97:
	s_sleep 6
	s_cbranch_execz .LBB0_100

.LBB0_113:
	s_sleep 6
	global_load_dword v2, v0, s[8:9] sc1
	s_or_b64 s[16:17], s[16:17], exec
	s_waitcnt vmcnt(0)
	v_cmp_eq_u32_e32 vcc, v2, v1
	s_and_saveexec_b64 s[18:19], vcc
	s_cbranch_execz .LBB0_112
	s_sleep 6
	global_load_dword v2, v0, s[8:9] sc1
	s_mov_b64 s[22:23], -1
	s_waitcnt vmcnt(0)
	v_cmp_eq_u32_e32 vcc, v2, v1
	s_and_saveexec_b64 s[20:21], vcc
	s_cbranch_execz .LBB0_111
	s_sleep 6
	global_load_dword v2, v0, s[8:9] sc1
	s_mov_b64 s[40:41], -1
	s_waitcnt vmcnt(0)
	v_cmp_eq_u32_e32 vcc, v2, v1
	s_and_saveexec_b64 s[22:23], vcc
	s_cbranch_execz .LBB0_110
	s_sleep 6
	global_load_dword v2, v0, s[8:9] sc1
	s_mov_b64 s[42:43], -1
	s_waitcnt vmcnt(0)
	v_cmp_eq_u32_e32 vcc, v2, v1
	s_and_saveexec_b64 s[40:41], vcc
	s_cbranch_execz .LBB0_109
	s_sleep 6
	global_load_dword v2, v0, s[8:9] sc1
	s_mov_b64 s[44:45], -1
	s_waitcnt vmcnt(0)
	v_cmp_eq_u32_e32 vcc, v2, v1
	s_and_saveexec_b64 s[42:43], vcc
	s_cbranch_execz .LBB0_108
	s_sleep 6
	global_load_dword v2, v0, s[8:9] sc1
	s_mov_b64 s[46:47], -1
	s_waitcnt vmcnt(0)
	v_cmp_eq_u32_e32 vcc, v2, v1
	s_and_saveexec_b64 s[44:45], vcc
	s_cbranch_execz .LBB0_107
	s_sleep 6
	global_load_dword v2, v0, s[8:9] sc1
	s_cmp_lg_u32 s3, 0
	s_cselect_b64 s[34:35], -1, 0
	s_waitcnt vmcnt(0)
	v_cmp_eq_u32_e32 vcc, v2, v1
	s_and_b64 s[34:35], vcc, s[34:35]
	s_and_saveexec_b64 s[48:49], s[34:35]
	s_cbranch_execz .LBB0_106
	s_sleep 6
	global_load_dword v2, v0, s[8:9] sc1
	s_add_i32 s3, s3, -8
	s_waitcnt vmcnt(0)
	v_cmp_ne_u32_e32 vcc, v2, v1
	s_orn2_b64 s[46:47], vcc, exec
	s_branch .LBB0_106

.LBB0_135:
	s_sleep 6
	global_load_dword v2, v0, s[6:7] sc1
	s_or_b64 s[16:17], s[16:17], exec
	s_waitcnt vmcnt(0)
	v_cmp_eq_u32_e32 vcc, v2, v1
	s_and_saveexec_b64 s[18:19], vcc
	s_cbranch_execz .LBB0_134
	s_sleep 6
	global_load_dword v2, v0, s[6:7] sc1
	s_mov_b64 s[22:23], -1
	s_waitcnt vmcnt(0)
	v_cmp_eq_u32_e32 vcc, v2, v1
	s_and_saveexec_b64 s[20:21], vcc
	s_cbranch_execz .LBB0_133
	s_sleep 6
	global_load_dword v2, v0, s[6:7] sc1
	s_mov_b64 s[40:41], -1
	s_waitcnt vmcnt(0)
	v_cmp_eq_u32_e32 vcc, v2, v1
	s_and_saveexec_b64 s[22:23], vcc
	s_cbranch_execz .LBB0_132
	s_sleep 6
	global_load_dword v2, v0, s[6:7] sc1
	s_mov_b64 s[42:43], -1
	s_waitcnt vmcnt(0)
	v_cmp_eq_u32_e32 vcc, v2, v1
	s_and_saveexec_b64 s[40:41], vcc
	s_cbranch_execz .LBB0_131
	s_sleep 6
	global_load_dword v2, v0, s[6:7] sc1
	s_mov_b64 s[44:45], -1
	s_waitcnt vmcnt(0)
	v_cmp_eq_u32_e32 vcc, v2, v1
	s_and_saveexec_b64 s[42:43], vcc
	s_cbranch_execz .LBB0_130
	s_sleep 6
	global_load_dword v2, v0, s[6:7] sc1
	s_mov_b64 s[46:47], -1
	s_waitcnt vmcnt(0)
	v_cmp_eq_u32_e32 vcc, v2, v1
	s_and_saveexec_b64 s[44:45], vcc
	s_cbranch_execz .LBB0_129
	s_sleep 6
	global_load_dword v2, v0, s[6:7] sc1
	s_cmp_lg_u32 s3, 0
	s_cselect_b64 s[34:35], -1, 0
	s_waitcnt vmcnt(0)
	v_cmp_eq_u32_e32 vcc, v2, v1
	s_and_b64 s[34:35], vcc, s[34:35]
	s_and_saveexec_b64 s[48:49], s[34:35]
	s_cbranch_execz .LBB0_128
	s_sleep 6
	global_load_dword v2, v0, s[6:7] sc1
	s_add_i32 s3, s3, -8
	s_waitcnt vmcnt(0)
	v_cmp_ne_u32_e32 vcc, v2, v1
	s_orn2_b64 s[46:47], vcc, exec
	s_branch .LBB0_128

.LBB0_177:
	s_sleep 6
	global_load_dword v2, v0, s[8:9] sc1
	s_or_b64 s[16:17], s[16:17], exec
	s_waitcnt vmcnt(0)
	v_cmp_eq_u32_e32 vcc, v2, v1
	s_and_saveexec_b64 s[18:19], vcc
	s_cbranch_execz .LBB0_176
	s_sleep 6
	global_load_dword v2, v0, s[8:9] sc1
	s_mov_b64 s[22:23], -1
	s_waitcnt vmcnt(0)
	v_cmp_eq_u32_e32 vcc, v2, v1
	s_and_saveexec_b64 s[20:21], vcc
	s_cbranch_execz .LBB0_175
	s_sleep 6
	global_load_dword v2, v0, s[8:9] sc1
	s_mov_b64 s[36:37], -1
	s_waitcnt vmcnt(0)
	v_cmp_eq_u32_e32 vcc, v2, v1
	s_and_saveexec_b64 s[22:23], vcc
	s_cbranch_execz .LBB0_174
	s_sleep 6
	global_load_dword v2, v0, s[8:9] sc1
	s_mov_b64 s[38:39], -1
	s_waitcnt vmcnt(0)
	v_cmp_eq_u32_e32 vcc, v2, v1
	s_and_saveexec_b64 s[36:37], vcc
	s_cbranch_execz .LBB0_173
	s_sleep 6
	global_load_dword v2, v0, s[8:9] sc1
	s_mov_b64 s[40:41], -1
	s_waitcnt vmcnt(0)
	v_cmp_eq_u32_e32 vcc, v2, v1
	s_and_saveexec_b64 s[38:39], vcc
	s_cbranch_execz .LBB0_172
	s_sleep 6
	global_load_dword v2, v0, s[8:9] sc1
	s_mov_b64 s[42:43], -1
	s_waitcnt vmcnt(0)
	v_cmp_eq_u32_e32 vcc, v2, v1
	s_and_saveexec_b64 s[40:41], vcc
	s_cbranch_execz .LBB0_171
	s_sleep 6
	global_load_dword v2, v0, s[8:9] sc1
	s_cmp_lg_u32 s3, 0
	s_cselect_b64 s[34:35], -1, 0
	s_waitcnt vmcnt(0)
	v_cmp_eq_u32_e32 vcc, v2, v1
	s_and_b64 s[34:35], vcc, s[34:35]
	s_and_saveexec_b64 s[44:45], s[34:35]
	s_cbranch_execz .LBB0_170
	s_sleep 6
	global_load_dword v2, v0, s[8:9] sc1
	s_add_i32 s3, s3, -8
	s_waitcnt vmcnt(0)
	v_cmp_ne_u32_e32 vcc, v2, v1
	s_orn2_b64 s[42:43], vcc, exec
	s_branch .LBB0_170

.LBB0_199:
	s_sleep 6
	global_load_dword v2, v0, s[6:7] sc1
	s_or_b64 s[16:17], s[16:17], exec
	s_waitcnt vmcnt(0)
	v_cmp_eq_u32_e32 vcc, v2, v1
	s_and_saveexec_b64 s[18:19], vcc
	s_cbranch_execz .LBB0_198
	s_sleep 6
	global_load_dword v2, v0, s[6:7] sc1
	s_mov_b64 s[22:23], -1
	s_waitcnt vmcnt(0)
	v_cmp_eq_u32_e32 vcc, v2, v1
	s_and_saveexec_b64 s[20:21], vcc
	s_cbranch_execz .LBB0_197
	s_sleep 6
	global_load_dword v2, v0, s[6:7] sc1
	s_mov_b64 s[36:37], -1
	s_waitcnt vmcnt(0)
	v_cmp_eq_u32_e32 vcc, v2, v1
	s_and_saveexec_b64 s[22:23], vcc
	s_cbranch_execz .LBB0_196
	s_sleep 6
	global_load_dword v2, v0, s[6:7] sc1
	s_mov_b64 s[38:39], -1
	s_waitcnt vmcnt(0)
	v_cmp_eq_u32_e32 vcc, v2, v1
	s_and_saveexec_b64 s[36:37], vcc
	s_cbranch_execz .LBB0_195
	s_sleep 6
	global_load_dword v2, v0, s[6:7] sc1
	s_mov_b64 s[40:41], -1
	s_waitcnt vmcnt(0)
	v_cmp_eq_u32_e32 vcc, v2, v1
	s_and_saveexec_b64 s[38:39], vcc
	s_cbranch_execz .LBB0_194
	s_sleep 6
	global_load_dword v2, v0, s[6:7] sc1
	s_mov_b64 s[42:43], -1
	s_waitcnt vmcnt(0)
	v_cmp_eq_u32_e32 vcc, v2, v1
	s_and_saveexec_b64 s[40:41], vcc
	s_cbranch_execz .LBB0_193
	s_sleep 6
	global_load_dword v2, v0, s[6:7] sc1
	s_cmp_lg_u32 s3, 0
	s_cselect_b64 s[34:35], -1, 0
	s_waitcnt vmcnt(0)
	v_cmp_eq_u32_e32 vcc, v2, v1
	s_and_b64 s[34:35], vcc, s[34:35]
	s_and_saveexec_b64 s[44:45], s[34:35]
	s_cbranch_execz .LBB0_192
	s_sleep 6
	global_load_dword v2, v0, s[6:7] sc1
	s_add_i32 s3, s3, -8
	s_waitcnt vmcnt(0)
	v_cmp_ne_u32_e32 vcc, v2, v1
	s_orn2_b64 s[42:43], vcc, exec
	s_branch .LBB0_192

.LBB0_787:
	s_sleep 6
	global_load_dword v2, v0, s[8:9] sc1
	s_or_b64 s[16:17], s[16:17], exec
	s_waitcnt vmcnt(0)
	v_cmp_eq_u32_e32 vcc, v2, v1
	s_and_saveexec_b64 s[18:19], vcc
	s_cbranch_execz .LBB0_786
	s_sleep 6
	global_load_dword v2, v0, s[8:9] sc1
	s_mov_b64 s[22:23], -1
	s_waitcnt vmcnt(0)
	v_cmp_eq_u32_e32 vcc, v2, v1
	s_and_saveexec_b64 s[20:21], vcc
	s_cbranch_execz .LBB0_785
	s_sleep 6
	global_load_dword v2, v0, s[8:9] sc1
	s_mov_b64 s[24:25], -1
	s_waitcnt vmcnt(0)
	v_cmp_eq_u32_e32 vcc, v2, v1
	s_and_saveexec_b64 s[22:23], vcc
	s_cbranch_execz .LBB0_784
	s_sleep 6
	global_load_dword v2, v0, s[8:9] sc1
	s_mov_b64 s[36:37], -1
	s_waitcnt vmcnt(0)
	v_cmp_eq_u32_e32 vcc, v2, v1
	s_and_saveexec_b64 s[24:25], vcc
	s_cbranch_execz .LBB0_783
	s_sleep 6
	global_load_dword v2, v0, s[8:9] sc1
	s_mov_b64 s[38:39], -1
	s_waitcnt vmcnt(0)
	v_cmp_eq_u32_e32 vcc, v2, v1
	s_and_saveexec_b64 s[36:37], vcc
	s_cbranch_execz .LBB0_782
	s_sleep 6
	global_load_dword v2, v0, s[8:9] sc1
	s_mov_b64 s[40:41], -1
	s_waitcnt vmcnt(0)
	v_cmp_eq_u32_e32 vcc, v2, v1
	s_and_saveexec_b64 s[38:39], vcc
	s_cbranch_execz .LBB0_781
	s_sleep 6
	global_load_dword v2, v0, s[8:9] sc1
	s_cmp_lg_u32 s3, 0
	s_cselect_b64 s[34:35], -1, 0
	s_waitcnt vmcnt(0)
	v_cmp_eq_u32_e32 vcc, v2, v1
	s_and_b64 s[34:35], vcc, s[34:35]
	s_and_saveexec_b64 s[42:43], s[34:35]
	s_cbranch_execz .LBB0_780
	s_sleep 6
	global_load_dword v2, v0, s[8:9] sc1
	s_add_i32 s3, s3, -8
	s_waitcnt vmcnt(0)
	v_cmp_ne_u32_e32 vcc, v2, v1
	s_orn2_b64 s[40:41], vcc, exec
	s_branch .LBB0_780

.LBB0_809:
	s_sleep 6
	global_load_dword v2, v0, s[6:7] sc1
	s_or_b64 s[16:17], s[16:17], exec
	s_waitcnt vmcnt(0)
	v_cmp_eq_u32_e32 vcc, v2, v1
	s_and_saveexec_b64 s[18:19], vcc
	s_cbranch_execz .LBB0_808
	s_sleep 6
	global_load_dword v2, v0, s[6:7] sc1
	s_mov_b64 s[22:23], -1
	s_waitcnt vmcnt(0)
	v_cmp_eq_u32_e32 vcc, v2, v1
	s_and_saveexec_b64 s[20:21], vcc
	s_cbranch_execz .LBB0_807
	s_sleep 6
	global_load_dword v2, v0, s[6:7] sc1
	s_mov_b64 s[24:25], -1
	s_waitcnt vmcnt(0)
	v_cmp_eq_u32_e32 vcc, v2, v1
	s_and_saveexec_b64 s[22:23], vcc
	s_cbranch_execz .LBB0_806
	s_sleep 6
	global_load_dword v2, v0, s[6:7] sc1
	s_mov_b64 s[36:37], -1
	s_waitcnt vmcnt(0)
	v_cmp_eq_u32_e32 vcc, v2, v1
	s_and_saveexec_b64 s[24:25], vcc
	s_cbranch_execz .LBB0_805
	s_sleep 6
	global_load_dword v2, v0, s[6:7] sc1
	s_mov_b64 s[38:39], -1
	s_waitcnt vmcnt(0)
	v_cmp_eq_u32_e32 vcc, v2, v1
	s_and_saveexec_b64 s[36:37], vcc
	s_cbranch_execz .LBB0_804
	s_sleep 6
	global_load_dword v2, v0, s[6:7] sc1
	s_mov_b64 s[40:41], -1
	s_waitcnt vmcnt(0)
	v_cmp_eq_u32_e32 vcc, v2, v1
	s_and_saveexec_b64 s[38:39], vcc
	s_cbranch_execz .LBB0_803
	s_sleep 6
	global_load_dword v2, v0, s[6:7] sc1
	s_cmp_lg_u32 s3, 0
	s_cselect_b64 s[34:35], -1, 0
	s_waitcnt vmcnt(0)
	v_cmp_eq_u32_e32 vcc, v2, v1
	s_and_b64 s[34:35], vcc, s[34:35]
	s_and_saveexec_b64 s[42:43], s[34:35]
	s_cbranch_execz .LBB0_802
	s_sleep 6
	global_load_dword v2, v0, s[6:7] sc1
	s_add_i32 s3, s3, -8
	s_waitcnt vmcnt(0)
	v_cmp_ne_u32_e32 vcc, v2, v1
	s_orn2_b64 s[40:41], vcc, exec
	s_branch .LBB0_802

.LBB0_979:
	s_sleep 6
	global_load_dword v2, v0, s[8:9] sc1
	s_or_b64 s[14:15], s[14:15], exec
	s_waitcnt vmcnt(0)
	v_cmp_eq_u32_e32 vcc, v2, v1
	s_and_saveexec_b64 s[16:17], vcc
	s_cbranch_execz .LBB0_978
	s_sleep 6
	global_load_dword v2, v0, s[8:9] sc1
	s_mov_b64 s[20:21], -1
	s_waitcnt vmcnt(0)
	v_cmp_eq_u32_e32 vcc, v2, v1
	s_and_saveexec_b64 s[18:19], vcc
	s_cbranch_execz .LBB0_977
	s_sleep 6
	global_load_dword v2, v0, s[8:9] sc1
	s_mov_b64 s[22:23], -1
	s_waitcnt vmcnt(0)
	v_cmp_eq_u32_e32 vcc, v2, v1
	s_and_saveexec_b64 s[20:21], vcc
	s_cbranch_execz .LBB0_976
	s_sleep 6
	global_load_dword v2, v0, s[8:9] sc1
	s_mov_b64 s[24:25], -1
	s_waitcnt vmcnt(0)
	v_cmp_eq_u32_e32 vcc, v2, v1
	s_and_saveexec_b64 s[22:23], vcc
	s_cbranch_execz .LBB0_975
	s_sleep 6
	global_load_dword v2, v0, s[8:9] sc1
	s_mov_b64 s[26:27], -1
	s_waitcnt vmcnt(0)
	v_cmp_eq_u32_e32 vcc, v2, v1
	s_and_saveexec_b64 s[24:25], vcc
	s_cbranch_execz .LBB0_974
	s_sleep 6
	global_load_dword v2, v0, s[8:9] sc1
	s_mov_b64 s[28:29], -1
	s_waitcnt vmcnt(0)
	v_cmp_eq_u32_e32 vcc, v2, v1
	s_and_saveexec_b64 s[26:27], vcc
	s_cbranch_execz .LBB0_973
	s_sleep 6
	global_load_dword v2, v0, s[8:9] sc1
	s_cmp_lg_u32 s3, 0
	s_cselect_b64 s[28:29], -1, 0
	s_waitcnt vmcnt(0)
	v_cmp_eq_u32_e32 vcc, v2, v1
	s_and_b64 s[34:35], vcc, s[28:29]
	s_mov_b64 s[28:29], -1
	s_and_saveexec_b64 s[30:31], s[34:35]
	s_cbranch_execz .LBB0_972
	s_sleep 6
	global_load_dword v2, v0, s[8:9] sc1
	s_add_i32 s3, s3, -8
	s_waitcnt vmcnt(0)
	v_cmp_ne_u32_e32 vcc, v2, v1
	s_orn2_b64 s[28:29], vcc, exec
	s_branch .LBB0_972

.LBB0_1001:
	s_sleep 6
	global_load_dword v2, v0, s[6:7] sc1
	s_or_b64 s[14:15], s[14:15], exec
	s_waitcnt vmcnt(0)
	v_cmp_eq_u32_e32 vcc, v2, v1
	s_and_saveexec_b64 s[16:17], vcc
	s_cbranch_execz .LBB0_1000
	s_sleep 6
	global_load_dword v2, v0, s[6:7] sc1
	s_mov_b64 s[20:21], -1
	s_waitcnt vmcnt(0)
	v_cmp_eq_u32_e32 vcc, v2, v1
	s_and_saveexec_b64 s[18:19], vcc
	s_cbranch_execz .LBB0_999
	s_sleep 6
	global_load_dword v2, v0, s[6:7] sc1
	s_mov_b64 s[22:23], -1
	s_waitcnt vmcnt(0)
	v_cmp_eq_u32_e32 vcc, v2, v1
	s_and_saveexec_b64 s[20:21], vcc
	s_cbranch_execz .LBB0_998
	s_sleep 6
	global_load_dword v2, v0, s[6:7] sc1
	s_mov_b64 s[24:25], -1
	s_waitcnt vmcnt(0)
	v_cmp_eq_u32_e32 vcc, v2, v1
	s_and_saveexec_b64 s[22:23], vcc
	s_cbranch_execz .LBB0_997
	s_sleep 6
	global_load_dword v2, v0, s[6:7] sc1
	s_mov_b64 s[26:27], -1
	s_waitcnt vmcnt(0)
	v_cmp_eq_u32_e32 vcc, v2, v1
	s_and_saveexec_b64 s[24:25], vcc
	s_cbranch_execz .LBB0_996
	s_sleep 6
	global_load_dword v2, v0, s[6:7] sc1
	s_mov_b64 s[28:29], -1
	s_waitcnt vmcnt(0)
	v_cmp_eq_u32_e32 vcc, v2, v1
	s_and_saveexec_b64 s[26:27], vcc
	s_cbranch_execz .LBB0_995
	s_sleep 6
	global_load_dword v2, v0, s[6:7] sc1
	s_cmp_lg_u32 s3, 0
	s_cselect_b64 s[28:29], -1, 0
	s_waitcnt vmcnt(0)
	v_cmp_eq_u32_e32 vcc, v2, v1
	s_and_b64 s[34:35], vcc, s[28:29]
	s_mov_b64 s[28:29], -1
	s_and_saveexec_b64 s[30:31], s[34:35]
	s_cbranch_execz .LBB0_994
	s_sleep 6
	global_load_dword v2, v0, s[6:7] sc1
	s_add_i32 s3, s3, -8
	s_waitcnt vmcnt(0)
	v_cmp_ne_u32_e32 vcc, v2, v1
	s_orn2_b64 s[28:29], vcc, exec
	s_branch .LBB0_994
